# natten item prologue de-serialised: all Q fragment loads and the first K/V tile loads in flight together (was five serial global round trips)
# speedup vs baseline: 1.0035x; 1.0002x over previous
.LBB0_343:
	s_or_b64 exec, exec, s[0:1]
	v_readlane_b32 s0, v253, 46
	s_ashr_i32 s0, s0, 7
	v_and_b32_e32 v3, 31, v2
	v_bfe_u32 v2, v2, 5, 1
	s_mov_b32 s90, s0
	s_lshl_b32 s0, s0, 4
	v_readlane_b32 s1, v253, 45
	v_lshl_or_b32 v190, v7, 6, v3
	v_lshl_or_b32 v0, v6, 5, v3
	s_or_b32 s4, s0, s1
	v_mul_lo_u32 v4, v0, s91
	v_lshlrev_b32_e32 v0, 4, v2
	v_ashrrev_i32_e32 v191, 31, v190
	v_add3_u32 v192, 0, v4, v0
	v_mad_i64_i32 v[4:5], s[0:1], s4, v198, v[190:191]
	v_readlane_b32 s0, v254, 3
	v_lshlrev_b64 v[4:5], 7, v[4:5]
	v_readlane_b32 s1, v254, 4
	s_add_i32 s96, s2, -4
	s_sub_i32 s2, s3, s2
	v_lshl_add_u64 v[4:5], s[0:1], 0, v[4:5]
	v_lshl_add_u64 v[4:5], v[4:5], 0, v[0:1]
	s_mov_b64 s[0:1], 0x1000
	v_lshl_add_u64 v[12:13], v[4:5], 0, s[0:1]
	s_movk_i32 s0, 0x1000
	v_add_co_u32_e32 v8, vcc, s0, v4
	global_load_dwordx4 v[130:133], v[4:5], off
	s_nop 0
	v_addc_co_u32_e32 v9, vcc, 0, v5, vcc
	global_load_dwordx4 v[158:161], v[8:9], off
	s_add_i32 s97, s2, 11
	s_mul_hi_i32 s0, s4, 0x48000
	s_mul_i32 s4, s4, 0x48000
	v_readlane_b32 s6, v254, 40
	v_readlane_b32 s7, v254, 41
	s_add_u32 s92, s6, s4
	s_addc_u32 s93, s7, s0
	v_readlane_b32 s1, v254, 1
	s_add_u32 s94, s1, s4
	v_readlane_b32 s1, v254, 2
	v_readlane_b32 s6, v255, 40
	s_addc_u32 s95, s1, s0
	v_readlane_b32 s7, v255, 41
	s_lshl_b32 s6, s96, 6
	s_lshl_b64 s[0:1], s[6:7], 7
	s_add_u32 s4, s92, s0
	s_addc_u32 s5, s93, s1
	s_lshl_b32 s0, s96, 7
	s_add_u32 s0, s94, s0
	s_addc_u32 s1, s95, 0
	s_movk_i32 s3, 0x1200
	v_lshlrev_b32_e32 v191, 2, v2
	global_load_dwordx4 v[134:137], v[4:5], off offset:32
	global_load_dwordx4 v[146:149], v[12:13], off offset:32
	global_load_dwordx4 v[138:141], v[4:5], off offset:64
	global_load_dwordx4 v[150:153], v[12:13], off offset:64
	global_load_dwordx4 v[142:145], v[4:5], off offset:96
	global_load_dwordx4 v[154:157], v[12:13], off offset:96
	v_mov_b32_e32 v4, v193
	s_nop 0
	v_ashrrev_i32_e32 v5, 31, v4
	v_lshl_add_u64 v[8:9], v[4:5], 4, s[4:5]
	global_load_dwordx4 v[8:11], v[8:9], off
	v_add_u32_e32 v20, 0x100, v4
	v_ashrrev_i32_e32 v21, 31, v20
	v_lshl_add_u64 v[12:13], v[20:21], 4, s[4:5]
	global_load_dwordx4 v[12:15], v[12:13], off
	v_lshlrev_b32_e32 v0, 4, v4
	v_and_b32_e32 v0, 0x70, v0
	v_lshl_add_u64 v[22:23], s[0:1], 0, v[0:1]
	v_ashrrev_i32_e32 v0, 3, v4
	v_mad_i64_i32 v[4:5], s[0:1], v0, s3, v[22:23]
	global_load_dwordx4 v[16:19], v[4:5], off
	v_ashrrev_i32_e32 v0, 3, v20
	v_mad_i64_i32 v[4:5], s[0:1], v0, s3, v[22:23]
	global_load_dwordx4 v[20:23], v[4:5], off
	v_mov_b32_e32 v4, v193
	s_nop 0
	v_ashrrev_i32_e32 v0, 31, v4
	v_lshrrev_b32_e32 v0, 29, v0
	v_add_u32_e32 v0, v4, v0
	v_lshrrev_b32_e32 v5, 3, v0
	v_and_b32_e32 v0, 0xffffff8, v0
	v_sub_u32_e32 v0, v4, v0
	v_mul_lo_u32 v5, v5, s91
	v_lshlrev_b32_e32 v0, 4, v0
	v_add3_u32 v0, 0, v5, v0
	s_waitcnt vmcnt(3)
	ds_write_b128 v192, v[158:161] offset:47104
	ds_write_b128 v192, v[146:149] offset:47136
	ds_write_b128 v192, v[150:153] offset:47168
	ds_write_b128 v192, v[154:157] offset:47200
	ds_write_b128 v0, v[8:11]
	v_add_u32_e32 v8, 0x100, v4
	v_ashrrev_i32_e32 v0, 31, v8
	v_lshrrev_b32_e32 v0, 29, v0
	v_add_u32_e32 v0, v8, v0
	v_lshrrev_b32_e32 v5, 3, v0
	v_and_b32_e32 v0, 0xffffff8, v0
	v_sub_u32_e32 v0, v8, v0
	v_mul_lo_u32 v5, v5, s91
	v_lshlrev_b32_e32 v0, 4, v0
	v_add3_u32 v0, 0, v5, v0
	s_waitcnt vmcnt(2)
	ds_write_b128 v0, v[12:15]
	v_lshlrev_b32_e32 v0, 4, v4
	v_and_b32_e32 v0, 0x70, v0
	v_add_u32_e32 v0, 0, v0
	v_lshrrev_b32_e32 v4, 3, v4
	v_mad_u64_u32 v[4:5], s[0:1], v4, s91, v[0:1]
	s_waitcnt vmcnt(1)
	ds_write_b128 v4, v[16:19] offset:13312
	v_lshrrev_b32_e32 v4, 3, v8
	v_mad_u64_u32 v[4:5], s[0:1], v4, s91, v[0:1]
	s_lshl_b32 s1, s97, 6
	s_or_b32 s0, s6, 64
	s_sub_i32 s1, 0x800, s1
	s_cmp_gt_i32 s2, -11
	s_cselect_b32 s6, s0, s1
	s_lshl_b64 s[0:1], s[6:7], 7
	s_waitcnt vmcnt(0)
	ds_write_b128 v4, v[20:23] offset:13312
	s_add_u32 s4, s92, s0
	v_mov_b32_e32 v4, v193
	s_addc_u32 s5, s93, s1
	s_mov_b32 s1, s7
	v_writelane_b32 v255, s0, 40
	v_ashrrev_i32_e32 v5, 31, v4
	v_lshl_add_u64 v[8:9], v[4:5], 4, s[4:5]
	v_writelane_b32 v255, s1, 41
	s_lshl_b64 s[0:1], s[6:7], 1
	global_load_dwordx4 v[146:149], v[8:9], off
	v_add_u32_e32 v8, 0x100, v4
	s_add_u32 s0, s94, s0
	v_ashrrev_i32_e32 v9, 31, v8
	v_lshlrev_b32_e32 v0, 4, v4
	s_addc_u32 s1, s95, s1
	v_lshl_add_u64 v[10:11], v[8:9], 4, s[4:5]
	v_and_b32_e32 v0, 0x70, v0
	global_load_dwordx4 v[150:153], v[10:11], off
	v_lshl_add_u64 v[10:11], s[0:1], 0, v[0:1]
	v_ashrrev_i32_e32 v0, 3, v4
	v_mad_i64_i32 v[4:5], s[0:1], v0, s3, v[10:11]
	v_ashrrev_i32_e32 v0, 3, v8
	global_load_dwordx4 v[154:157], v[4:5], off
	v_mad_i64_i32 v[4:5], s[0:1], v0, s3, v[10:11]
	global_load_dwordx4 v[158:161], v[4:5], off
	s_mov_b64 s[0:1], -1
	s_cmp_gt_i32 s2, -16
	s_waitcnt lgkmcnt(0)
	s_barrier
	s_cbranch_scc1 .LBB0_345
	v_lshlrev_b32_e32 v66, 2, v2
	s_mov_b64 s[0:1], 0
